# v5 + phase 9 tile steps visited 4,3,2,1,0,5..10 (oldest still-cached G tiles first) run 1
# speedup vs baseline: 1.0156x; 1.0156x over previous
;     __device__ bool next(int i, Unit& u) const {
;         const long L = (long)i * G + c; if (L >= nwg) return false;
;         int wgid = (int)L; { const int q = nwg / NXCD, r = nwg % NXCD, xcd = wgid % NXCD, off = wgid / NXCD; wgid = (xcd < r ? xcd * (q + 1) : r * (q + 1) + (xcd - r) * q) + off; }
;         const int nig = WGM * nN, gid = wgid / nig, fm = gid * WGM, gsz = (nM - fm) < WGM ? (nM - fm) : WGM;
; template <class Epi, class Sched, bool SP2 = PG8_SP2>
; __device__ __forceinline__ void gemm_phase(LAS unsigned char* lds, const Gemm g, const Sched& S, const Epi& E) {
;     const int tid = threadIdx.x, wid = __builtin_amdgcn_readfirstlane(tid >> 6), lane = tid & 63, wr = wid >> 2, wc = wid & 3, fr = lane & 15, fq = lane >> 4;
;     const int K = g.K, nt = K / BK, lda = g.lda;
;     unsigned voffA[2], voffB[2];
; #pragma unroll
;     for (int i = 0; i < 2; ++i) { int R, C; stage_rc(tid * 16 + i * 8192, R, C); const int Rb = Epi::PERM ? ((R & ~31) + perm32(R & 31)) : R;
;         voffA[i] = (unsigned)(R * lda + C) * 2u; voffB[i] = (unsigned)(Rb * K + C) * 2u; }
;     const size_t kstep = (size_t)(BK * 2);
;     const size_t hstepA = (size_t)HALF * lda * 2, hstepB = (size_t)HALF * K * 2;
;     const size_t tstepA = 2 * hstepA, tstepB = 2 * hstepB;
;     const unsigned ldsw = (unsigned)wid * 1024u;
;     const int aoff = lds_byte(wr * 64 + fr, fq * 8), boff = lds_byte(wc * 32 + fr, fq * 8);
;     ...
;     Unit cur, nxt; int ui = 0;
;     if (!S.next(0, cur)) return;
;     f32x4 acc[2][2][4][2];
; #pragma unroll
;     for (int a = 0; a < 2; ++a)
; #pragma unroll
;         for (int b = 0; b < 2; ++b)
; #pragma unroll
;             for (int m = 0; m < 4; ++m)
; #pragma unroll
;                 for (int n = 0; n < 2; ++n) acc[a][b][m][n] = (f32x4){0.f, 0.f, 0.f, 0.f};
;     bf16x8 At[4][2], B0[2][2], B1[2][2];
;     const char* cA = (const char*)g.A + (size_t)cur.pm * tstepA; const char* cB = (const char*)g.Bt + (size_t)cur.pn * tstepB;
;     if constexpr (SP2) {
;     PG8_STAGE(PG8_SB(0, 0), cB, voffB); PG8_STAGE(PG8_SB(0, 1), cB + hstepB, voffB); PG8_STAGE(PG8_SA(0, 0), cA, voffA); PG8_STAGE(PG8_SA(0, 1), cA + hstepA, voffA);
;     if (wr == 1) PG8_BAR;
;     PG8_WAIT_V(2); PG8_BAR;
;     PG8_STAGE(PG8_SB(1, 0), cB + kstep, voffB); PG8_STAGE(PG8_SA(1, 0), cA + kstep, voffA); PG8_STAGE(PG8_SB(1, 1), cB + hstepB + kstep, voffB);
;     PG8_WAIT_V(6); PG8_BAR;
.LBB0_993:
	v_readlane_b32 s2, v240, 5
	v_readlane_b32 s3, v240, 6
	s_cmp_lt_i32 s2, 10
	s_cselect_b64 s[2:3], -1, 0
	s_waitcnt lgkmcnt(0)
	s_and_b64 s[10:11], s[2:3], s[0:1]
	s_andn2_b64 vcc, exec, s[10:11]
	s_cbranch_vccnz .LBB0_1014
	s_cmpk_gt_i32 s88, 0xaff
	v_readfirstlane_b32 s2, v222
	s_cbranch_scc1 .LBB0_1014
	s_load_dwordx2 s[4:5], s[78:79], 0xc0
	v_lshrrev_b32_e32 v0, 5, v222
	v_lshrrev_b32_e32 v2, 1, v222
	v_and_b32_e32 v0, 4, v0
	v_bfe_u32 v1, v222, 2, 2
	v_and_b32_e32 v11, 24, v2
	v_or3_b32 v0, v0, v1, v11
	v_lshlrev_b32_e32 v1, 4, v222
	v_add_u32_e32 v8, 0x2000, v1
	v_lshrrev_b32_e32 v2, 7, v8
	s_movk_i32 s0, 0xe0
	v_and_b32_e32 v4, 32, v222
	s_waitcnt lgkmcnt(0)
	s_add_u32 s33, s4, 0x8000000
	v_and_or_b32 v3, v2, s0, v0
	v_bitop3_b32 v9, v1, v4, 48 bitop3:0x6c
	v_and_b32_e32 v10, 64, v222
	v_bfe_u32 v12, v222, 2, 4
	s_movk_i32 s0, 0xf0
	s_addc_u32 s44, s5, 0
	v_or_b32_e32 v1, v9, v10
	v_and_or_b32 v2, v2, s0, v12
	s_add_u32 s45, s4, 0x3000000
	v_lshl_or_b32 v188, v2, 12, v1
	v_lshrrev_b32_e32 v2, 3, v222
	s_movk_i32 s0, 0x60
	s_addc_u32 s46, s5, 0
	v_and_or_b32 v0, v2, s0, v0
	s_movk_i32 s0, 0x70
	s_ashr_i32 s48, s88, 31
	v_lshl_or_b32 v190, v0, 12, v1
	v_and_or_b32 v0, v2, s0, v12
	s_lshr_b32 s0, s48, 29
	s_add_i32 s0, s88, s0
	s_lshr_b32 s24, s2, 6
	s_ashr_i32 s1, s0, 3
	s_and_b32 s0, s0, -8
	s_lshr_b32 s3, s2, 8
	s_lshl_b32 s47, s24, 10
	s_sub_i32 s0, s88, s0
	s_cmp_lt_i32 s0, 0
	s_movk_i32 s49, 0x161
	s_cselect_b32 s6, s49, 0x160
	s_mul_i32 s0, s6, s0
	s_add_i32 s0, s0, s1
	s_addk_i32 s0, 0x80
	s_mul_hi_i32 s1, s0, 0x2e8ba2e9
	s_lshr_b32 s6, s1, 31
	s_ashr_i32 s1, s1, 5
	s_add_i32 s1, s1, s6
	s_lshl_b32 s6, s1, 3
	s_mulk_i32 s1, 0xb0
	s_sub_i32 s0, s0, s1
	s_sext_i32_i16 s1, s0
	s_bfe_u32 s1, s1, 0x3001c
	s_add_i32 s1, s0, s1
	s_sext_i32_i16 s7, s1
	s_and_b32 s1, s1, 0xfff8
	s_sub_i32 s0, s0, s1
	s_sext_i32_i16 s0, s0
	s_lshr_b32 s26, s7, 3
	s_add_i32 s6, s6, s0
	s_ashr_i32 s7, s6, 31
	s_bfe_i64 s[8:9], s[26:27], 0x100000
	s_lshl_b64 s[0:1], s[6:7], 20
	s_lshl_b64 s[8:9], s[8:9], 20
	s_add_u32 s8, s45, s8
	s_addc_u32 s9, s46, s9
	s_add_i32 s50, s47, 0
	s_add_i32 m0, s50, 0x10000
	v_lshl_or_b32 v186, v3, 12, v1
	global_load_lds_dwordx4 v190, s[8:9]
	s_add_i32 m0, s50, 0x12000
	s_add_u32 s12, s8, 0x80000
	global_load_lds_dwordx4 v186, s[8:9]
	s_addc_u32 s13, s9, 0
	s_add_i32 m0, s50, 0x14000
	v_lshl_or_b32 v192, v0, 12, v1
	global_load_lds_dwordx4 v190, s[12:13]
	s_add_i32 m0, s50, 0x16000
	s_add_u32 s0, s33, s0
	s_addc_u32 s1, s44, s1
	s_add_i32 s51, s50, 0x2000
	global_load_lds_dwordx4 v186, s[12:13]
	s_mov_b32 m0, s50
	s_add_u32 s12, s0, 0x80000
	global_load_lds_dwordx4 v192, s[0:1]
	s_mov_b32 m0, s51
	s_addc_u32 s13, s1, 0
	s_add_i32 s52, s50, 0x4000
	global_load_lds_dwordx4 v188, s[0:1]
	s_mov_b32 m0, s52
	s_add_i32 s53, s50, 0x6000
	global_load_lds_dwordx4 v192, s[12:13]
	s_mov_b32 m0, s53
	v_mov_b32_e32 v191, 0
	global_load_lds_dwordx4 v188, s[12:13]
	s_load_dwordx4 s[12:15], s[78:79], 0xa0
	v_mov_b32_e32 v187, v191
	v_mov_b32_e32 v193, v191
	v_mov_b32_e32 v189, v191
	s_cmp_eq_u32 s3, 1
	s_mov_b32 s54, 0
	v_lshl_add_u64 v[6:7], s[8:9], 0, v[190:191]
	v_lshl_add_u64 v[4:5], s[8:9], 0, v[186:187]
	v_lshl_add_u64 v[0:1], s[0:1], 0, v[192:193]
	s_cselect_b64 s[16:17], -1, 0
	s_cmp_lg_u32 s3, 1
	v_lshl_add_u64 v[2:3], s[0:1], 0, v[188:189]
	s_cbranch_scc1 .LBB0_997
	s_barrier

;     __device__ bool next(int i, Unit& u) const {
;         const long L = (long)i * G + c; if (L >= nwg) return false;
;         int wgid = (int)L; { const int q = nwg / NXCD, r = nwg % NXCD, xcd = wgid % NXCD, off = wgid / NXCD; wgid = (xcd < r ? xcd * (q + 1) : r * (q + 1) + (xcd - r) * q) + off; }
;         const int nig = WGM * nN, gid = wgid / nig, fm = gid * WGM, gsz = (nM - fm) < WGM ? (nM - fm) : WGM;
;         u.pm = fm + ((wgid % nig) % gsz); u.pn = (wgid % nig) / gsz; return true;
;     }
; template <class Epi, class Sched, bool SP2 = PG8_SP2>
; __device__ __forceinline__ void gemm_phase(LAS unsigned char* lds, const Gemm g, const Sched& S, const Epi& E) {
;     ...
;         const bool has_next = S.next(ui + 1, nxt);
;         const char* nA = has_next ? (const char*)g.A + (size_t)nxt.pm * tstepA : cA; const char* nB = has_next ? (const char*)g.Bt + (size_t)nxt.pn * tstepB : cB;
.LBB0_1000:
	s_add_i32 s54, s54, 1
	s_sub_i32 s2, 4, s54
	s_cmp_lt_i32 s2, 0
	s_cselect_b32 s2, s54, s2
	s_mul_i32 s3, s2, s86
	s_add_i32 s36, s3, s88
	s_cmp_gt_i32 s54, 10
	s_cselect_b32 s36, 0xb00, s36
	s_mov_b32 s37, 0
	v_cmp_gt_i64_e32 vcc, s[36:37], v[200:201]
	v_cmp_lt_i64_e64 s[4:5], s[36:37], v[198:199]
	s_cbranch_vccnz .LBB0_1002
	s_ashr_i32 s2, s36, 31
	s_lshr_b32 s2, s2, 29
	s_add_i32 s2, s36, s2
	s_ashr_i32 s3, s2, 3
	s_and_b32 s2, s2, -8
	s_sub_i32 s2, s36, s2
	s_cmp_lt_i32 s2, 0
	s_cselect_b32 s34, s49, 0x160
	s_mul_i32 s2, s34, s2
	s_add_i32 s2, s2, s3
	s_mul_hi_i32 s3, s2, 0x2e8ba2e9
	s_lshr_b32 s34, s3, 31
	s_ashr_i32 s3, s3, 5
	s_add_i32 s3, s3, s34
	s_lshl_b32 s35, s3, 3
	s_sub_i32 s34, 0x80, s35
	s_min_i32 s36, s34, 8
	s_abs_i32 s34, s36
	v_cvt_f32_u32_e32 v0, s34
	s_sub_i32 s38, 0, s34
	s_mulk_i32 s3, 0xb0
	s_sub_i32 s2, s2, s3
	v_rcp_iflag_f32_e32 v0, v0
	s_abs_i32 s3, s2
	s_xor_b32 s37, s2, s36
	s_ashr_i32 s37, s37, 31
	v_mul_f32_e32 v0, 0x4f7ffffe, v0
	v_cvt_u32_f32_e32 v0, v0
	s_nop 0
	v_readfirstlane_b32 s39, v0
	s_mul_i32 s38, s38, s39
	s_mul_hi_u32 s38, s39, s38
	s_add_i32 s39, s39, s38
	s_mul_hi_u32 s38, s3, s39
	s_mul_i32 s39, s38, s34
	s_sub_i32 s3, s3, s39
	s_add_i32 s40, s38, 1
	s_sub_i32 s39, s3, s34
	s_cmp_ge_u32 s3, s34
	s_cselect_b32 s38, s40, s38
	s_cselect_b32 s3, s39, s3
	s_add_i32 s39, s38, 1
	s_cmp_ge_u32 s3, s34
	s_cselect_b32 s3, s39, s38
	s_xor_b32 s3, s3, s37
	s_sub_i32 s34, s3, s37
	s_mul_i32 s3, s34, s36
	s_sub_i32 s2, s2, s3
	s_add_i32 s38, s2, s35
